# attention loop: 32-bit pointer bumps instead of 64-bit v_lshl_add_u64 (on top of v038)
# speedup vs baseline: 1.0022x; 1.0022x over previous
; DEVFI void partialSM2(f32x16& p0, f32x16& p1, float& mhat, f32x16& negm, float& alpha, const float thr2, const bool first) {
;     ...
; #pragma unroll
;     for (int r = 0; r < 16; ++r) p0[r] = __builtin_amdgcn_exp2f(p0[r]);
; }
; DEVFI void finishSM(f32x16& p0, f32x16& p1, float alpha, float& l_reg, bf16x8& pa0, bf16x8& pa1, bf16x8& pa2, bf16x8& pa3) {
; #pragma unroll
;     for (int r = 0; r < 16; ++r) p1[r] = __builtin_amdgcn_exp2f(p1[r]);
;     float ps = 0;
; #pragma unroll
;     for (int r = 0; r < 16; ++r) ps += p0[r];
; #pragma unroll
;     for (int r = 0; r < 16; ++r) ps += p1[r];
;     { auto rr = __builtin_amdgcn_permlane32_swap(__float_as_uint(ps), __float_as_uint(ps), false, false);
;       ps = __uint_as_float(rr[0]) + __uint_as_float(rr[1]); }
;     l_reg = l_reg * alpha + ps;
.LBB0_1173:
	v_exp_f32_e32 v203, v94
	v_exp_f32_e32 v205, v95
	v_exp_f32_e32 v189, v96
	v_exp_f32_e32 v204, v97
	v_exp_f32_e32 v187, v98
	v_exp_f32_e32 v202, v99
	v_exp_f32_e32 v186, v100
	v_exp_f32_e32 v188, v101
	v_exp_f32_e32 v183, v102
	v_exp_f32_e32 v185, v103
	v_exp_f32_e32 v163, v104
	v_exp_f32_e32 v184, v105
	v_exp_f32_e32 v161, v106
	v_exp_f32_e32 v182, v107
	v_exp_f32_e32 v160, v108
	v_exp_f32_e32 v162, v109
	v_add_f32_e32 v0, v13, v180
	v_fmac_f32_e32 v0, v179, v166
	v_add_f32_e32 v166, v90, v91
	v_fmac_f32_e32 v166, v0, v181
	v_add_u32_e32 v154, 0x30000, v154
	v_add_u32_e32 v156, 0x20000, v156
	v_add_u32_e32 v158, 0x30000, v158
	s_add_i32 s18, s18, 2
	s_and_b64 vcc, exec, s[0:1]
	s_waitcnt lgkmcnt(0)
	s_barrier
	s_cbranch_vccnz .LBB0_1175
	v_mov_b32_e32 v179, v8
	s_branch .LBB0_1151
